# GU (gate/up) GEMM tiles: LDS-DMA staging (global_load_lds_dwordx4 into unpadded XOR-swizzled LDS, 2 stages), no VGPR staging or ds_write, software-pipelined fragment reads
# speedup vs baseline: 1.0217x; 1.0180x over previous
.LBB0_53:
	s_mul_hi_i32 s2, s10, 0x2e8ba2e9
	s_lshr_b32 s3, s2, 31
	s_ashr_i32 s2, s2, 5
	s_add_i32 s17, s2, s3
	s_lshl_b32 s2, s17, 3
	s_sub_i32 s3, s0, s2
	s_min_i32 s3, s3, 8
	s_abs_i32 s14, s3
	v_cvt_f32_u32_e32 v2, s14
	s_sub_i32 s19, 0, s14
	s_mul_i32 s15, s17, 0xffffff50
	s_add_i32 s15, s15, s10
	v_rcp_iflag_f32_e32 v2, v2
	s_abs_i32 s16, s15
	s_xor_b32 s18, s15, s3
	s_ashr_i32 s18, s18, 31
	v_mul_f32_e32 v2, 0x4f7ffffe, v2
	v_cvt_u32_f32_e32 v2, v2
	s_mulk_i32 s17, 0xa8
	s_mov_b32 s4, 0x308d000
	s_mov_b32 s6, 0x30ad000
	v_readfirstlane_b32 s22, v2
	s_mul_i32 s19, s19, s22
	s_mul_hi_u32 s19, s22, s19
	s_add_i32 s22, s22, s19
	s_mul_hi_u32 s19, s16, s22
	s_mul_i32 s22, s19, s14
	s_sub_i32 s16, s16, s22
	s_add_i32 s23, s19, 1
	s_sub_i32 s22, s16, s14
	s_cmp_ge_u32 s16, s14
	s_cselect_b32 s19, s23, s19
	s_cselect_b32 s16, s22, s16
	s_add_i32 s22, s19, 1
	s_cmp_ge_u32 s16, s14
	s_cselect_b32 s14, s22, s19
	s_xor_b32 s14, s14, s18
	s_sub_i32 s16, s14, s18
	s_mul_i32 s18, s16, s3
	s_add_i32 s15, s15, s2
	s_sub_i32 s2, s15, s18
	s_lshl_b32 s14, s2, 8
	v_add_u32_e32 v2, s14, v164
	v_ashrrev_i32_e32 v3, 31, v2
	v_lshlrev_b64 v[2:3], 11, v[2:3]
	s_lshl_b32 s15, s16, 8
	v_lshl_add_u64 v[52:53], v[168:169], 0, v[2:3]
	s_mov_b32 s2, 0x20000
	v_add_u32_e32 v4, s15, v164
	v_add_co_u32_e32 v54, vcc, s2, v52
	v_ashrrev_i32_e32 v5, 31, v4
	s_nop 0
	v_addc_co_u32_e32 v55, vcc, 0, v53, vcc
	s_mov_b32 s3, 0x40000
	v_lshlrev_b64 v[48:49], 11, v[4:5]
	v_add_co_u32_e32 v56, vcc, s3, v52
	v_lshl_add_u64 v[50:51], v[166:167], 0, v[48:49]
	s_nop 0
	v_addc_co_u32_e32 v57, vcc, 0, v53, vcc
	v_add_co_u32_e32 v58, vcc, s2, v50
	s_mov_b32 s2, 0x60000
	s_nop 0
	v_addc_co_u32_e32 v59, vcc, 0, v51, vcc
	v_add_co_u32_e32 v60, vcc, s3, v50
	v_addc_co_u32_e32 v61, vcc, 0, v51, vcc
	v_add_co_u32_e32 v62, vcc, s2, v50
	v_addc_co_u32_e32 v63, vcc, 0, v51, vcc
	v_add_co_u32_e32 v64, vcc, s2, v52
	v_addc_co_u32_e32 v65, vcc, 0, v53, vcc
	s_sub_i32 s18, s10, s18
	s_sub_i32 s17, s18, s17
	s_lshl_b32 s18, s17, 8
	s_ashr_i32 s19, s18, 31
	v_lshl_add_u64 v[178:179], v[174:175], 0, v[48:49]
	v_lshl_add_u64 v[48:49], v[164:165], 0, s[18:19]
	v_mov_b32_e32 v2, 0
	v_lshlrev_b64 v[48:49], 11, v[48:49]
	s_mov_b32 s16, 1
	s_mov_b64 s[2:3], 0
	v_mov_b32_e32 v3, v2
	v_mov_b32_e32 v4, v2
	v_mov_b32_e32 v5, v2
	v_mov_b32_e32 v6, v2
	v_mov_b32_e32 v7, v2
	v_mov_b32_e32 v8, v2
	v_mov_b32_e32 v9, v2
	v_mov_b32_e32 v10, v2
	v_mov_b32_e32 v11, v2
	v_mov_b32_e32 v12, v2
	v_mov_b32_e32 v13, v2
	v_mov_b32_e32 v14, v2
	v_mov_b32_e32 v15, v2
	v_lshl_add_u64 v[180:181], v[176:177], 0, v[48:49]
	v_mov_b32_e32 v48, v2
	v_mov_b32_e32 v49, v2
	v_mov_b32_e32 v50, v2
	v_mov_b32_e32 v51, v2
	v_mov_b32_e32 v52, v2
	v_mov_b32_e32 v53, v2
	v_mov_b32_e32 v54, v2
	v_mov_b32_e32 v55, v2
	v_mov_b32_e32 v56, v2
	v_mov_b32_e32 v57, v2
	v_mov_b32_e32 v58, v2
	v_mov_b32_e32 v59, v2
	v_mov_b32_e32 v60, v2
	v_mov_b32_e32 v61, v2
	v_mov_b32_e32 v62, v2
	v_mov_b32_e32 v63, v2
	v_mov_b32_e32 v16, v2
	v_mov_b32_e32 v17, v2
	v_mov_b32_e32 v34, v2
	v_mov_b32_e32 v35, v2
	v_mov_b32_e32 v36, v2
	v_mov_b32_e32 v37, v2
	v_mov_b32_e32 v38, v2
	v_mov_b32_e32 v39, v2
	v_mov_b32_e32 v40, v2
	v_mov_b32_e32 v41, v2
	v_mov_b32_e32 v42, v2
	v_mov_b32_e32 v43, v2
	v_mov_b32_e32 v44, v2
	v_mov_b32_e32 v45, v2
	v_mov_b32_e32 v46, v2
	v_mov_b32_e32 v47, v2
	v_mov_b32_e32 v18, v2
	v_mov_b32_e32 v19, v2
	v_mov_b32_e32 v20, v2
	v_mov_b32_e32 v21, v2
	v_mov_b32_e32 v22, v2
	v_mov_b32_e32 v23, v2
	v_mov_b32_e32 v24, v2
	v_mov_b32_e32 v25, v2
	v_mov_b32_e32 v26, v2
	v_mov_b32_e32 v27, v2
	v_mov_b32_e32 v28, v2
	v_mov_b32_e32 v29, v2
	v_mov_b32_e32 v30, v2
	v_mov_b32_e32 v31, v2
	v_mov_b32_e32 v32, v2
	v_mov_b32_e32 v33, v2
	v_mov_b32_e32 v64, v2
	v_mov_b32_e32 v65, v2
	v_mov_b32_e32 v66, v2
	v_mov_b32_e32 v67, v2
	v_mov_b32_e32 v68, v2
	v_mov_b32_e32 v69, v2
	v_mov_b32_e32 v70, v2
	v_mov_b32_e32 v71, v2
	v_mov_b32_e32 v72, v2
	v_mov_b32_e32 v73, v2
	v_mov_b32_e32 v74, v2
	v_mov_b32_e32 v75, v2
	v_mov_b32_e32 v76, v2
	v_mov_b32_e32 v77, v2
	v_mov_b32_e32 v78, v2
	v_mov_b32_e32 v79, v2
	v_mov_b32_e32 v80, v2
	v_mov_b32_e32 v81, v2
	v_mov_b32_e32 v98, v2
	v_mov_b32_e32 v99, v2
	v_mov_b32_e32 v100, v2
	v_mov_b32_e32 v101, v2
	v_mov_b32_e32 v102, v2
	v_mov_b32_e32 v103, v2
	v_mov_b32_e32 v104, v2
	v_mov_b32_e32 v105, v2
	v_mov_b32_e32 v106, v2
	v_mov_b32_e32 v107, v2
	v_mov_b32_e32 v108, v2
	v_mov_b32_e32 v109, v2
	v_mov_b32_e32 v110, v2
	v_mov_b32_e32 v111, v2
	v_mov_b32_e32 v112, v2
	v_mov_b32_e32 v113, v2
	v_mov_b32_e32 v82, v2
	v_mov_b32_e32 v83, v2
	v_mov_b32_e32 v84, v2
	v_mov_b32_e32 v85, v2
	v_mov_b32_e32 v86, v2
	v_mov_b32_e32 v87, v2
	v_mov_b32_e32 v88, v2
	v_mov_b32_e32 v89, v2
	v_mov_b32_e32 v90, v2
	v_mov_b32_e32 v91, v2
	v_mov_b32_e32 v92, v2
	v_mov_b32_e32 v93, v2
	v_mov_b32_e32 v94, v2
	v_mov_b32_e32 v95, v2
	v_mov_b32_e32 v96, v2
	v_mov_b32_e32 v97, v2
	v_mov_b32_e32 v114, v2
	v_mov_b32_e32 v115, v2
	v_mov_b32_e32 v116, v2
	v_mov_b32_e32 v117, v2
	v_mov_b32_e32 v118, v2
	v_mov_b32_e32 v119, v2
	v_mov_b32_e32 v120, v2
	v_mov_b32_e32 v121, v2
	v_mov_b32_e32 v122, v2
	v_mov_b32_e32 v123, v2
	v_mov_b32_e32 v124, v2
	v_mov_b32_e32 v125, v2
	v_mov_b32_e32 v126, v2
	v_mov_b32_e32 v127, v2
	v_mov_b32_e32 v128, v2
	v_mov_b32_e32 v129, v2
	s_mov_b32 s7, 0x30cd000
	s_waitcnt lgkmcnt(0)
	v_lshrrev_b32_e32 v140, 6, v231
	v_and_b32_e32 v141, 63, v231
	v_readfirstlane_b32 s17, v140
	s_and_b32 s18, s17, 3
	s_lshl_b32 s19, s18, 6
	s_lshl_b32 s4, s18, 13
	s_cmp_lt_u32 s17, 4
	s_cbranch_scc0 .Lgud_bload
	s_add_i32 s6, s14, s19
	s_add_u32 s2, s36, 0x308d800
	s_addc_u32 s3, s37, 0
	s_branch .Lgud_have
.Lgud_bload:
	s_add_i32 s6, s15, s19
	v_readlane_b32 s7, v255, 30
	s_nop 3
	s_mul_i32 s7, s7, 0xb00000
	s_add_u32 s2, s36, s7
	s_addc_u32 s3, s37, 0
	s_add_u32 s2, s2, 0xc6d800
	s_addc_u32 s3, s3, 0
	s_add_u32 s4, s4, 0x8000
.Lgud_have:
	s_lshl_b32 s6, s6, 11
	s_add_u32 s2, s2, s6
	s_addc_u32 s3, s3, 0
	v_lshrrev_b32_e32 v142, 3, v141
	v_lshlrev_b32_e32 v142, 11, v142
	v_and_b32_e32 v143, 7, v141
	v_lshrrev_b32_e32 v144, 4, v141
	v_xor_b32_e32 v143, v143, v144
	v_lshlrev_b32_e32 v143, 4, v143
	v_or_b32_e32 v138, v142, v143
	v_xor_b32_e32 v139, 64, v138
	v_and_b32_e32 v142, 31, v141
	v_lshrrev_b32_e32 v143, 5, v141
	v_bfe_u32 v144, v142, 1, 3
	v_and_b32_e32 v145, 1, v144
	v_xor_b32_e32 v143, v143, v145
	v_lshlrev_b32_e32 v143, 4, v143
	v_lshl_add_u32 v143, v142, 7, v143
	v_and_b32_e32 v144, 6, v144
	s_lshr_b32 s6, s17, 2
	s_lshl_b32 s6, s6, 14
	s_lshl_b32 s7, s18, 13
	s_add_u32 s7, s7, 0x8000
	v_xor_b32_e32 v145, 0, v144
	v_lshl_add_u32 v145, v145, 4, v143
	v_add_u32_e32 v130, s6, v145
	v_add_u32_e32 v134, s7, v145
	v_xor_b32_e32 v145, 2, v144
	v_lshl_add_u32 v145, v145, 4, v143
	v_add_u32_e32 v131, s6, v145
	v_add_u32_e32 v135, s7, v145
	v_xor_b32_e32 v145, 4, v144
	v_lshl_add_u32 v145, v145, 4, v143
	v_add_u32_e32 v132, s6, v145
	v_add_u32_e32 v136, s7, v145
	v_xor_b32_e32 v145, 6, v144
	v_lshl_add_u32 v145, v145, 4, v143
	v_add_u32_e32 v133, s6, v145
	v_add_u32_e32 v137, s7, v145
	s_mov_b32 m0, s4
	s_nop 0
	global_load_lds_dwordx4 v138, s[2:3]
	s_add_u32 m0, m0, 0x400
	s_add_u32 s2, s2, 0x4000
	s_addc_u32 s3, s3, 0
	global_load_lds_dwordx4 v139, s[2:3]
	s_add_u32 m0, m0, 0x400
	s_add_u32 s2, s2, 0x4000
	s_addc_u32 s3, s3, 0
	global_load_lds_dwordx4 v138, s[2:3]
	s_add_u32 m0, m0, 0x400
	s_add_u32 s2, s2, 0x4000
	s_addc_u32 s3, s3, 0
	global_load_lds_dwordx4 v139, s[2:3]
	s_add_u32 m0, m0, 0x400
	s_add_u32 s2, s2, 0x4000
	s_addc_u32 s3, s3, 0
	global_load_lds_dwordx4 v138, s[2:3]
	s_add_u32 m0, m0, 0x400
	s_add_u32 s2, s2, 0x4000
	s_addc_u32 s3, s3, 0
	global_load_lds_dwordx4 v139, s[2:3]
	s_add_u32 m0, m0, 0x400
	s_add_u32 s2, s2, 0x4000
	s_addc_u32 s3, s3, 0
	global_load_lds_dwordx4 v138, s[2:3]
	s_add_u32 m0, m0, 0x400
	s_add_u32 s2, s2, 0x4000
	s_addc_u32 s3, s3, 0
	global_load_lds_dwordx4 v139, s[2:3]
	s_sub_u32 s2, s2, 0x1bf80
	s_subb_u32 s3, s3, 0
	s_xor_b32 s4, s4, 0x10000
	s_mov_b32 s16, 0
	s_waitcnt vmcnt(0)
	s_barrier
.LBB0_54:
	s_cmp_lt_u32 s16, 15
	s_cbranch_scc0 .Lgud_nodma
	s_mov_b32 m0, s4
	s_nop 0
	global_load_lds_dwordx4 v138, s[2:3]
	s_add_u32 m0, m0, 0x400
	s_add_u32 s2, s2, 0x4000
	s_addc_u32 s3, s3, 0
	global_load_lds_dwordx4 v139, s[2:3]
	s_add_u32 m0, m0, 0x400
	s_add_u32 s2, s2, 0x4000
	s_addc_u32 s3, s3, 0
	global_load_lds_dwordx4 v138, s[2:3]
	s_add_u32 m0, m0, 0x400
	s_add_u32 s2, s2, 0x4000
	s_addc_u32 s3, s3, 0
	global_load_lds_dwordx4 v139, s[2:3]
	s_add_u32 m0, m0, 0x400
	s_add_u32 s2, s2, 0x4000
	s_addc_u32 s3, s3, 0
	global_load_lds_dwordx4 v138, s[2:3]
	s_add_u32 m0, m0, 0x400
	s_add_u32 s2, s2, 0x4000
	s_addc_u32 s3, s3, 0
	global_load_lds_dwordx4 v139, s[2:3]
	s_add_u32 m0, m0, 0x400
	s_add_u32 s2, s2, 0x4000
	s_addc_u32 s3, s3, 0
	global_load_lds_dwordx4 v138, s[2:3]
	s_add_u32 m0, m0, 0x400
	s_add_u32 s2, s2, 0x4000
	s_addc_u32 s3, s3, 0
	global_load_lds_dwordx4 v139, s[2:3]
	s_sub_u32 s2, s2, 0x1bf80
	s_subb_u32 s3, s3, 0
	s_xor_b32 s4, s4, 0x10000
.Lgud_nodma:
	ds_read_b128 v[192:195], v134
	ds_read_b128 v[208:211], v130
	ds_read_b128 v[196:199], v134 offset:4096
	ds_read_b128 v[218:221], v130 offset:4096
	ds_read_b128 v[222:225], v130 offset:8192
	ds_read_b128 v[244:247], v130 offset:12288
	s_waitcnt lgkmcnt(4)
	v_mfma_f32_32x32x16_bf16 v[114:129], v[192:195], v[208:211], v[114:129]
	s_waitcnt lgkmcnt(3)
	v_mfma_f32_32x32x16_bf16 v[98:113], v[196:199], v[208:211], v[98:113]
	ds_read_b128 v[232:235], v135
	ds_read_b128 v[240:243], v131
	ds_read_b128 v[236:239], v135 offset:4096
	s_waitcnt lgkmcnt(5)
	v_mfma_f32_32x32x16_bf16 v[82:97], v[192:195], v[218:221], v[82:97]
	v_mfma_f32_32x32x16_bf16 v[66:81], v[196:199], v[218:221], v[66:81]
	s_waitcnt lgkmcnt(4)
	v_mfma_f32_32x32x16_bf16 v[50:65], v[192:195], v[222:225], v[50:65]
	v_mfma_f32_32x32x16_bf16 v[34:49], v[196:199], v[222:225], v[34:49]
	s_waitcnt lgkmcnt(3)
	v_mfma_f32_32x32x16_bf16 v[18:33], v[192:195], v[244:247], v[18:33]
	v_mfma_f32_32x32x16_bf16 v[2:17], v[196:199], v[244:247], v[2:17]
	ds_read_b128 v[218:221], v131 offset:4096
	ds_read_b128 v[222:225], v131 offset:8192
	ds_read_b128 v[244:247], v131 offset:12288
	s_waitcnt lgkmcnt(3)
	v_mfma_f32_32x32x16_bf16 v[114:129], v[232:235], v[240:243], v[114:129]
	v_mfma_f32_32x32x16_bf16 v[98:113], v[236:239], v[240:243], v[98:113]
	ds_read_b128 v[192:195], v136
	ds_read_b128 v[208:211], v132
	ds_read_b128 v[196:199], v136 offset:4096
	s_waitcnt lgkmcnt(5)
	v_mfma_f32_32x32x16_bf16 v[82:97], v[232:235], v[218:221], v[82:97]
	v_mfma_f32_32x32x16_bf16 v[66:81], v[236:239], v[218:221], v[66:81]
	s_waitcnt lgkmcnt(4)
	v_mfma_f32_32x32x16_bf16 v[50:65], v[232:235], v[222:225], v[50:65]
	v_mfma_f32_32x32x16_bf16 v[34:49], v[236:239], v[222:225], v[34:49]
	s_waitcnt lgkmcnt(3)
	v_mfma_f32_32x32x16_bf16 v[18:33], v[232:235], v[244:247], v[18:33]
	v_mfma_f32_32x32x16_bf16 v[2:17], v[236:239], v[244:247], v[2:17]
	ds_read_b128 v[218:221], v132 offset:4096
	ds_read_b128 v[222:225], v132 offset:8192
	ds_read_b128 v[244:247], v132 offset:12288
	s_waitcnt lgkmcnt(3)
	v_mfma_f32_32x32x16_bf16 v[114:129], v[192:195], v[208:211], v[114:129]
	v_mfma_f32_32x32x16_bf16 v[98:113], v[196:199], v[208:211], v[98:113]
	ds_read_b128 v[232:235], v137
	ds_read_b128 v[240:243], v133
	ds_read_b128 v[236:239], v137 offset:4096
	s_waitcnt lgkmcnt(5)
	v_mfma_f32_32x32x16_bf16 v[82:97], v[192:195], v[218:221], v[82:97]
	v_mfma_f32_32x32x16_bf16 v[66:81], v[196:199], v[218:221], v[66:81]
	s_waitcnt lgkmcnt(4)
	v_mfma_f32_32x32x16_bf16 v[50:65], v[192:195], v[222:225], v[50:65]
	v_mfma_f32_32x32x16_bf16 v[34:49], v[196:199], v[222:225], v[34:49]
	s_waitcnt lgkmcnt(3)
	v_mfma_f32_32x32x16_bf16 v[18:33], v[192:195], v[244:247], v[18:33]
	v_mfma_f32_32x32x16_bf16 v[2:17], v[196:199], v[244:247], v[2:17]
	ds_read_b128 v[218:221], v133 offset:4096
	ds_read_b128 v[222:225], v133 offset:8192
	ds_read_b128 v[244:247], v133 offset:12288
	s_waitcnt lgkmcnt(3)
	v_mfma_f32_32x32x16_bf16 v[114:129], v[232:235], v[240:243], v[114:129]
	v_mfma_f32_32x32x16_bf16 v[98:113], v[236:239], v[240:243], v[98:113]
	s_waitcnt lgkmcnt(2)
	v_mfma_f32_32x32x16_bf16 v[82:97], v[232:235], v[218:221], v[82:97]
	v_mfma_f32_32x32x16_bf16 v[66:81], v[236:239], v[218:221], v[66:81]
	s_waitcnt lgkmcnt(1)
	v_mfma_f32_32x32x16_bf16 v[50:65], v[232:235], v[222:225], v[50:65]
	v_mfma_f32_32x32x16_bf16 v[34:49], v[236:239], v[222:225], v[34:49]
	s_waitcnt lgkmcnt(0)
	v_mfma_f32_32x32x16_bf16 v[18:33], v[232:235], v[244:247], v[18:33]
	v_mfma_f32_32x32x16_bf16 v[2:17], v[236:239], v[244:247], v[2:17]
	s_waitcnt vmcnt(0)
	s_barrier
	v_xor_b32_e32 v130, 0x10000, v130
	v_xor_b32_e32 v131, 0x10000, v131
	v_xor_b32_e32 v132, 0x10000, v132
	v_xor_b32_e32 v133, 0x10000, v133
	v_xor_b32_e32 v134, 0x10000, v134
	v_xor_b32_e32 v135, 0x10000, v135
	v_xor_b32_e32 v136, 0x10000, v136
	v_xor_b32_e32 v137, 0x10000, v137
	s_add_i32 s16, s16, 1
	s_cmp_lt_u32 s16, 16
	s_cbranch_scc1 .LBB0_54
	s_nop 15
	s_nop 15
	s_waitcnt lgkmcnt(3)
	s_waitcnt lgkmcnt(2)
	s_waitcnt lgkmcnt(1)
	s_waitcnt lgkmcnt(0)
	s_waitcnt lgkmcnt(0)
	s_waitcnt lgkmcnt(3)
	s_waitcnt lgkmcnt(2)
	s_waitcnt lgkmcnt(1)
	s_waitcnt lgkmcnt(0)
	s_waitcnt lgkmcnt(0)
	s_waitcnt lgkmcnt(3)
	s_waitcnt lgkmcnt(2)
	s_waitcnt lgkmcnt(1)
	s_waitcnt lgkmcnt(0)
	s_waitcnt lgkmcnt(0)
	v_add_u32_e32 v150, 0x12000, v170
	s_waitcnt lgkmcnt(3)
	s_waitcnt lgkmcnt(2)
	s_waitcnt lgkmcnt(1)
	s_waitcnt lgkmcnt(0)
	s_waitcnt lgkmcnt(0)
	s_waitcnt lgkmcnt(1)
	s_waitcnt lgkmcnt(0)
	s_waitcnt lgkmcnt(0)
	s_waitcnt lgkmcnt(3)
	s_waitcnt lgkmcnt(2)
	s_waitcnt lgkmcnt(1)
	s_waitcnt lgkmcnt(0)
	s_waitcnt lgkmcnt(0)
	s_waitcnt lgkmcnt(3)
	s_waitcnt lgkmcnt(2)
	s_waitcnt lgkmcnt(1)
	s_waitcnt lgkmcnt(0)
	s_waitcnt lgkmcnt(0)
	s_waitcnt lgkmcnt(0)
	s_add_i32 s10, s10, s46
	s_cmp_ge_i32 s10, s1
	s_nop 7
	v_mul_f32_e32 v137, 0xbfb8aa3b, v114
	v_exp_f32_e32 v137, v137
	v_add_u32_e32 v136, s14, v182
	v_add_f32_e32 v137, 1.0, v137
	v_rcp_f32_e32 v138, v137
	v_mul_f32_e32 v137, 0xbfb8aa3b, v115
	v_exp_f32_e32 v137, v137
	s_nop 0
	v_add_f32_e32 v137, 1.0, v137
	v_rcp_f32_e32 v139, v137
	v_or_b32_e32 v130, s15, v173
	v_ashrrev_i32_e32 v132, 1, v130
	v_ashrrev_i32_e32 v133, 31, v132
	v_pk_mul_f32 v[114:115], v[114:115], v[138:139]
	v_mov_b64_e32 v[130:131], s[40:41]
	v_mad_i64_i32 v[134:135], s[2:3], v136, s5, v[130:131]
	s_nop 4
	v_pk_mul_f32 v[114:115], v[98:99], v[114:115]
	v_mul_f32_e32 v98, 0xbfb8aa3b, v116
	v_mul_f32_e32 v99, 0xbfb8aa3b, v117
	v_exp_f32_e32 v98, v98
	v_exp_f32_e32 v99, v99
	v_cvt_pk_bf16_f32 v114, v114, v115
	v_add_f32_e32 v98, 1.0, v98
	v_add_f32_e32 v99, 1.0, v99
	v_rcp_f32_e32 v98, v98
	v_rcp_f32_e32 v99, v99
	s_nop 0
	v_pk_mul_f32 v[98:99], v[116:117], v[98:99]
	s_nop 0
	v_pk_mul_f32 v[100:101], v[100:101], v[98:99]
	v_mul_f32_e32 v98, 0xbfb8aa3b, v118
	v_mul_f32_e32 v99, 0xbfb8aa3b, v119
	v_exp_f32_e32 v98, v98
	v_exp_f32_e32 v99, v99
	v_cvt_pk_bf16_f32 v115, v100, v101
	v_add_f32_e32 v98, 1.0, v98
	v_add_f32_e32 v99, 1.0, v99
	v_rcp_f32_e32 v98, v98
	v_rcp_f32_e32 v99, v99
	s_nop 0
	v_pk_mul_f32 v[98:99], v[118:119], v[98:99]
	s_nop 0
	v_pk_mul_f32 v[102:103], v[102:103], v[98:99]
	v_mul_f32_e32 v98, 0xbfb8aa3b, v120
	v_cvt_pk_bf16_f32 v100, v102, v103
	v_mul_f32_e32 v102, 0xbfb8aa3b, v82
	v_mul_f32_e32 v103, 0xbfb8aa3b, v83
	v_exp_f32_e32 v102, v102
	v_exp_f32_e32 v103, v103
	v_mul_f32_e32 v99, 0xbfb8aa3b, v121
	v_exp_f32_e32 v98, v98
	v_add_f32_e32 v102, 1.0, v102
	v_add_f32_e32 v103, 1.0, v103
	v_rcp_f32_e32 v102, v102
	v_rcp_f32_e32 v103, v103
	v_exp_f32_e32 v99, v99
	v_add_f32_e32 v98, 1.0, v98
	v_rcp_f32_e32 v98, v98
	v_pk_mul_f32 v[82:83], v[82:83], v[102:103]
	v_add_f32_e32 v99, 1.0, v99
	v_pk_mul_f32 v[66:67], v[66:67], v[82:83]
	v_mul_f32_e32 v82, 0xbfb8aa3b, v84
	v_mul_f32_e32 v83, 0xbfb8aa3b, v85
	v_exp_f32_e32 v82, v82
	v_exp_f32_e32 v83, v83
	v_cvt_pk_bf16_f32 v66, v66, v67
	v_rcp_f32_e32 v99, v99
	v_add_f32_e32 v82, 1.0, v82
	v_add_f32_e32 v83, 1.0, v83
	v_rcp_f32_e32 v82, v82
	v_rcp_f32_e32 v83, v83
	v_pk_mul_f32 v[98:99], v[120:121], v[98:99]
	v_pk_mul_f32 v[82:83], v[84:85], v[82:83]
	s_nop 0
	v_pk_mul_f32 v[68:69], v[68:69], v[82:83]
	v_mul_f32_e32 v82, 0xbfb8aa3b, v86
	v_cvt_pk_bf16_f32 v67, v68, v69
	v_mul_f32_e32 v68, 0xbfb8aa3b, v50
	v_mul_f32_e32 v69, 0xbfb8aa3b, v51
	v_exp_f32_e32 v68, v68
	v_exp_f32_e32 v69, v69
	v_mul_f32_e32 v83, 0xbfb8aa3b, v87
	v_exp_f32_e32 v82, v82
	v_add_f32_e32 v68, 1.0, v68
	v_add_f32_e32 v69, 1.0, v69
	v_rcp_f32_e32 v68, v68
	v_rcp_f32_e32 v69, v69
	v_exp_f32_e32 v83, v83
	v_add_f32_e32 v82, 1.0, v82
	v_rcp_f32_e32 v82, v82
	v_pk_mul_f32 v[50:51], v[50:51], v[68:69]
	v_add_f32_e32 v83, 1.0, v83
	v_pk_mul_f32 v[34:35], v[34:35], v[50:51]
	v_mul_f32_e32 v50, 0xbfb8aa3b, v52
	v_mul_f32_e32 v51, 0xbfb8aa3b, v53
	v_exp_f32_e32 v50, v50
	v_exp_f32_e32 v51, v51
	v_cvt_pk_bf16_f32 v34, v34, v35
	v_rcp_f32_e32 v83, v83
	v_add_f32_e32 v50, 1.0, v50
	v_add_f32_e32 v51, 1.0, v51
	v_rcp_f32_e32 v50, v50
	v_rcp_f32_e32 v51, v51
	v_pk_mul_f32 v[82:83], v[86:87], v[82:83]
	v_pk_mul_f32 v[104:105], v[104:105], v[98:99]
	v_pk_mul_f32 v[70:71], v[70:71], v[82:83]
	v_pk_mul_f32 v[50:51], v[52:53], v[50:51]
	v_mul_f32_e32 v82, 0xbfb8aa3b, v88
	v_pk_mul_f32 v[36:37], v[36:37], v[50:51]
	v_mul_f32_e32 v50, 0xbfb8aa3b, v54
	v_cvt_pk_bf16_f32 v35, v36, v37
	v_mul_f32_e32 v36, 0xbfb8aa3b, v18
	v_mul_f32_e32 v37, 0xbfb8aa3b, v19
	v_exp_f32_e32 v36, v36
	v_exp_f32_e32 v37, v37
	v_mul_f32_e32 v51, 0xbfb8aa3b, v55
	v_exp_f32_e32 v50, v50
	v_add_f32_e32 v36, 1.0, v36
	v_add_f32_e32 v37, 1.0, v37
	v_rcp_f32_e32 v36, v36
	v_rcp_f32_e32 v37, v37
	v_exp_f32_e32 v51, v51
	v_mul_f32_e32 v83, 0xbfb8aa3b, v89
	v_exp_f32_e32 v82, v82
	v_pk_mul_f32 v[18:19], v[18:19], v[36:37]
	v_exp_f32_e32 v83, v83
	v_pk_mul_f32 v[2:3], v[2:3], v[18:19]
	v_mul_f32_e32 v18, 0xbfb8aa3b, v20
	v_mul_f32_e32 v19, 0xbfb8aa3b, v21
	v_exp_f32_e32 v18, v18
	v_exp_f32_e32 v19, v19
	v_add_f32_e32 v50, 1.0, v50
	v_add_f32_e32 v51, 1.0, v51
	v_add_f32_e32 v18, 1.0, v18
	v_add_f32_e32 v19, 1.0, v19
	v_rcp_f32_e32 v18, v18
	v_rcp_f32_e32 v19, v19
	v_rcp_f32_e32 v50, v50
	v_rcp_f32_e32 v51, v51
	v_mul_f32_e32 v98, 0xbfb8aa3b, v122
	v_pk_mul_f32 v[18:19], v[20:21], v[18:19]
	v_mul_f32_e32 v99, 0xbfb8aa3b, v123
	v_pk_mul_f32 v[4:5], v[4:5], v[18:19]
	v_mul_f32_e32 v18, 0xbfb8aa3b, v22
	v_mul_f32_e32 v19, 0xbfb8aa3b, v23
	v_exp_f32_e32 v18, v18
	v_exp_f32_e32 v19, v19
	v_exp_f32_e32 v98, v98
	v_exp_f32_e32 v99, v99
	v_add_f32_e32 v82, 1.0, v82
	v_add_f32_e32 v83, 1.0, v83
	v_rcp_f32_e32 v82, v82
	v_rcp_f32_e32 v83, v83
	v_pk_mul_f32 v[50:51], v[54:55], v[50:51]
	v_add_f32_e32 v18, 1.0, v18
	v_pk_mul_f32 v[38:39], v[38:39], v[50:51]
	v_mul_f32_e32 v50, 0xbfb8aa3b, v56
	v_mul_f32_e32 v51, 0xbfb8aa3b, v57
	v_exp_f32_e32 v50, v50
	v_exp_f32_e32 v51, v51
	v_add_f32_e32 v19, 1.0, v19
	v_add_f32_e32 v98, 1.0, v98
	v_add_f32_e32 v99, 1.0, v99
	v_rcp_f32_e32 v18, v18
	v_rcp_f32_e32 v19, v19
	v_rcp_f32_e32 v98, v98
	v_rcp_f32_e32 v99, v99
	v_pk_mul_f32 v[82:83], v[88:89], v[82:83]
	v_add_f32_e32 v50, 1.0, v50
	v_pk_mul_f32 v[72:73], v[72:73], v[82:83]
	v_mul_f32_e32 v82, 0xbfb8aa3b, v90
	v_mul_f32_e32 v83, 0xbfb8aa3b, v91
	v_exp_f32_e32 v82, v82
	v_exp_f32_e32 v83, v83
	v_add_f32_e32 v51, 1.0, v51
	v_rcp_f32_e32 v50, v50
	v_rcp_f32_e32 v51, v51
	v_pk_mul_f32 v[18:19], v[22:23], v[18:19]
	v_pk_mul_f32 v[98:99], v[122:123], v[98:99]
	v_pk_mul_f32 v[6:7], v[6:7], v[18:19]
	v_mul_f32_e32 v18, 0xbfb8aa3b, v24
	v_mul_f32_e32 v19, 0xbfb8aa3b, v25
	v_pk_mul_f32 v[106:107], v[106:107], v[98:99]
	v_mul_f32_e32 v98, 0xbfb8aa3b, v124
	v_mul_f32_e32 v99, 0xbfb8aa3b, v125
	v_exp_f32_e32 v18, v18
	v_exp_f32_e32 v19, v19
	v_exp_f32_e32 v98, v98
	v_exp_f32_e32 v99, v99
	v_add_f32_e32 v82, 1.0, v82
	v_add_f32_e32 v83, 1.0, v83
	v_rcp_f32_e32 v82, v82
	v_rcp_f32_e32 v83, v83
	v_pk_mul_f32 v[50:51], v[56:57], v[50:51]
	v_add_f32_e32 v18, 1.0, v18
	v_pk_mul_f32 v[40:41], v[40:41], v[50:51]
	v_mul_f32_e32 v50, 0xbfb8aa3b, v58
	v_mul_f32_e32 v51, 0xbfb8aa3b, v59
	v_exp_f32_e32 v50, v50
	v_exp_f32_e32 v51, v51
	v_add_f32_e32 v19, 1.0, v19
	v_add_f32_e32 v98, 1.0, v98
	v_add_f32_e32 v99, 1.0, v99
	v_rcp_f32_e32 v18, v18
	v_rcp_f32_e32 v19, v19
	v_rcp_f32_e32 v98, v98
	v_rcp_f32_e32 v99, v99
	v_pk_mul_f32 v[82:83], v[90:91], v[82:83]
	v_add_f32_e32 v50, 1.0, v50
	v_pk_mul_f32 v[74:75], v[74:75], v[82:83]
	v_mul_f32_e32 v82, 0xbfb8aa3b, v92
	v_mul_f32_e32 v83, 0xbfb8aa3b, v93
	v_exp_f32_e32 v82, v82
	v_exp_f32_e32 v83, v83
	v_add_f32_e32 v51, 1.0, v51
	v_rcp_f32_e32 v50, v50
	v_rcp_f32_e32 v51, v51
	v_pk_mul_f32 v[18:19], v[24:25], v[18:19]
	v_pk_mul_f32 v[98:99], v[124:125], v[98:99]
	v_pk_mul_f32 v[8:9], v[8:9], v[18:19]
	v_mul_f32_e32 v18, 0xbfb8aa3b, v26
	v_mul_f32_e32 v19, 0xbfb8aa3b, v27
	v_pk_mul_f32 v[108:109], v[108:109], v[98:99]
	v_mul_f32_e32 v98, 0xbfb8aa3b, v126
	v_mul_f32_e32 v99, 0xbfb8aa3b, v127
	v_exp_f32_e32 v18, v18
	v_exp_f32_e32 v19, v19
	v_exp_f32_e32 v98, v98
	v_exp_f32_e32 v99, v99
	v_add_f32_e32 v82, 1.0, v82
	v_add_f32_e32 v83, 1.0, v83
	v_rcp_f32_e32 v82, v82
	v_rcp_f32_e32 v83, v83
	v_pk_mul_f32 v[50:51], v[58:59], v[50:51]
	v_add_f32_e32 v18, 1.0, v18
	v_pk_mul_f32 v[42:43], v[42:43], v[50:51]
	v_mul_f32_e32 v50, 0xbfb8aa3b, v60
	v_mul_f32_e32 v51, 0xbfb8aa3b, v61
	v_exp_f32_e32 v50, v50
	v_exp_f32_e32 v51, v51
	v_add_f32_e32 v19, 1.0, v19
	v_add_f32_e32 v98, 1.0, v98
	v_add_f32_e32 v99, 1.0, v99
	v_rcp_f32_e32 v18, v18
	v_rcp_f32_e32 v19, v19
	v_rcp_f32_e32 v98, v98
	v_rcp_f32_e32 v99, v99
	v_pk_mul_f32 v[82:83], v[92:93], v[82:83]
	v_add_f32_e32 v50, 1.0, v50
	v_pk_mul_f32 v[76:77], v[76:77], v[82:83]
	v_mul_f32_e32 v82, 0xbfb8aa3b, v94
	v_mul_f32_e32 v83, 0xbfb8aa3b, v95
	v_exp_f32_e32 v82, v82
	v_exp_f32_e32 v83, v83
	v_add_f32_e32 v51, 1.0, v51
	v_rcp_f32_e32 v50, v50
	v_rcp_f32_e32 v51, v51
	v_pk_mul_f32 v[18:19], v[26:27], v[18:19]
	v_pk_mul_f32 v[98:99], v[126:127], v[98:99]
	v_pk_mul_f32 v[10:11], v[10:11], v[18:19]
	v_mul_f32_e32 v18, 0xbfb8aa3b, v28
	v_mul_f32_e32 v19, 0xbfb8aa3b, v29
	v_pk_mul_f32 v[110:111], v[110:111], v[98:99]
	v_mul_f32_e32 v98, 0xbfb8aa3b, v128
	v_mul_f32_e32 v99, 0xbfb8aa3b, v129
	v_exp_f32_e32 v18, v18
	v_exp_f32_e32 v19, v19
	v_exp_f32_e32 v98, v98
	v_exp_f32_e32 v99, v99
	v_add_f32_e32 v82, 1.0, v82
	v_add_f32_e32 v83, 1.0, v83
	v_rcp_f32_e32 v82, v82
	v_rcp_f32_e32 v83, v83
	v_pk_mul_f32 v[50:51], v[60:61], v[50:51]
	v_add_f32_e32 v18, 1.0, v18
	v_pk_mul_f32 v[44:45], v[44:45], v[50:51]
	v_mul_f32_e32 v50, 0xbfb8aa3b, v62
	v_mul_f32_e32 v51, 0xbfb8aa3b, v63
	v_exp_f32_e32 v50, v50
	v_exp_f32_e32 v51, v51
	v_add_f32_e32 v19, 1.0, v19
	v_add_f32_e32 v98, 1.0, v98
	v_add_f32_e32 v99, 1.0, v99
	v_rcp_f32_e32 v18, v18
	v_rcp_f32_e32 v19, v19
	v_rcp_f32_e32 v98, v98
	v_rcp_f32_e32 v99, v99
	v_pk_mul_f32 v[82:83], v[94:95], v[82:83]
	v_add_f32_e32 v50, 1.0, v50
	v_pk_mul_f32 v[78:79], v[78:79], v[82:83]
	v_mul_f32_e32 v82, 0xbfb8aa3b, v96
	v_mul_f32_e32 v83, 0xbfb8aa3b, v97
	v_exp_f32_e32 v82, v82
	v_exp_f32_e32 v83, v83
	v_add_f32_e32 v51, 1.0, v51
	v_rcp_f32_e32 v50, v50
	v_rcp_f32_e32 v51, v51
	v_pk_mul_f32 v[18:19], v[28:29], v[18:19]
	v_pk_mul_f32 v[98:99], v[128:129], v[98:99]
	v_pk_mul_f32 v[12:13], v[12:13], v[18:19]
	v_mul_f32_e32 v18, 0xbfb8aa3b, v30
	v_mul_f32_e32 v19, 0xbfb8aa3b, v31
	v_pk_mul_f32 v[112:113], v[112:113], v[98:99]
	v_lshlrev_b64 v[98:99], 1, v[132:133]
	v_exp_f32_e32 v18, v18
	v_exp_f32_e32 v19, v19
	v_lshl_add_u64 v[116:117], v[134:135], 0, v[98:99]
	v_add_f32_e32 v82, 1.0, v82
	v_add_f32_e32 v83, 1.0, v83
	v_lshl_add_u64 v[116:117], v[116:117], 0, v[0:1]
	v_cvt_pk_bf16_f32 v101, v104, v105
	v_rcp_f32_e32 v82, v82
	v_rcp_f32_e32 v83, v83
	v_pk_mul_f32 v[50:51], v[62:63], v[50:51]
	global_store_dwordx2 v[116:117], v[100:101], off offset:16
	v_cvt_pk_bf16_f32 v100, v106, v107
	v_cvt_pk_bf16_f32 v101, v108, v109
	v_pk_mul_f32 v[46:47], v[46:47], v[50:51]
	v_mul_f32_e32 v50, 0xbfb8aa3b, v64
	v_mul_f32_e32 v51, 0xbfb8aa3b, v65
	global_store_dwordx2 v[116:117], v[100:101], off offset:32
	v_cvt_pk_bf16_f32 v100, v110, v111
	v_cvt_pk_bf16_f32 v101, v112, v113
	v_exp_f32_e32 v50, v50
	v_exp_f32_e32 v51, v51
	v_add_f32_e32 v18, 1.0, v18
	v_add_f32_e32 v19, 1.0, v19
	global_store_dwordx2 v[116:117], v[100:101], off offset:48
	v_or_b32_e32 v100, 32, v136
	v_rcp_f32_e32 v18, v18
	v_rcp_f32_e32 v19, v19
	v_mad_i64_i32 v[100:101], s[2:3], v100, s5, v[130:131]
	v_pk_mul_f32 v[82:83], v[96:97], v[82:83]
	v_add_f32_e32 v50, 1.0, v50
	v_pk_mul_f32 v[80:81], v[80:81], v[82:83]
	v_lshl_add_u64 v[82:83], v[100:101], 0, v[98:99]
	v_lshl_add_u64 v[82:83], v[82:83], 0, v[0:1]
	v_add_f32_e32 v51, 1.0, v51
	global_store_dwordx2 v[82:83], v[66:67], off
	v_cvt_pk_bf16_f32 v66, v70, v71
	v_cvt_pk_bf16_f32 v67, v72, v73
	v_rcp_f32_e32 v50, v50
	v_rcp_f32_e32 v51, v51
	v_pk_mul_f32 v[18:19], v[30:31], v[18:19]
	global_store_dwordx2 v[82:83], v[66:67], off offset:16
	v_cvt_pk_bf16_f32 v66, v74, v75
	v_cvt_pk_bf16_f32 v67, v76, v77
	v_pk_mul_f32 v[14:15], v[14:15], v[18:19]
	v_mul_f32_e32 v18, 0xbfb8aa3b, v32
	v_mul_f32_e32 v19, 0xbfb8aa3b, v33
	global_store_dwordx2 v[82:83], v[66:67], off offset:32
	v_cvt_pk_bf16_f32 v66, v78, v79
	v_cvt_pk_bf16_f32 v67, v80, v81
	v_exp_f32_e32 v18, v18
	v_exp_f32_e32 v19, v19
	global_store_dwordx2 v[82:83], v[66:67], off offset:48
	v_or_b32_e32 v66, 64, v136
	v_mad_i64_i32 v[66:67], s[2:3], v66, s5, v[130:131]
	v_pk_mul_f32 v[50:51], v[64:65], v[50:51]
	v_add_f32_e32 v18, 1.0, v18
	v_pk_mul_f32 v[48:49], v[48:49], v[50:51]
	v_lshl_add_u64 v[50:51], v[66:67], 0, v[98:99]
	v_lshl_add_u64 v[50:51], v[50:51], 0, v[0:1]
	v_add_f32_e32 v19, 1.0, v19
	global_store_dwordx2 v[50:51], v[34:35], off
	v_cvt_pk_bf16_f32 v34, v38, v39
	v_cvt_pk_bf16_f32 v35, v40, v41
	v_rcp_f32_e32 v18, v18
	v_rcp_f32_e32 v19, v19
	global_store_dwordx2 v[50:51], v[34:35], off offset:16
	v_cvt_pk_bf16_f32 v34, v42, v43
	v_cvt_pk_bf16_f32 v35, v44, v45
	global_store_dwordx2 v[50:51], v[34:35], off offset:32
	v_cvt_pk_bf16_f32 v34, v46, v47
	v_cvt_pk_bf16_f32 v35, v48, v49
	global_store_dwordx2 v[50:51], v[34:35], off offset:48
	v_or_b32_e32 v34, 0x60, v136
	v_mad_i64_i32 v[34:35], s[2:3], v34, s5, v[130:131]
	v_pk_mul_f32 v[18:19], v[32:33], v[18:19]
	v_cvt_pk_bf16_f32 v2, v2, v3
	v_pk_mul_f32 v[16:17], v[16:17], v[18:19]
	v_lshl_add_u64 v[18:19], v[34:35], 0, v[98:99]
	v_lshl_add_u64 v[18:19], v[18:19], 0, v[0:1]
	v_cvt_pk_bf16_f32 v3, v4, v5
	global_store_dwordx2 v[18:19], v[2:3], off
	v_cvt_pk_bf16_f32 v2, v6, v7
	v_cvt_pk_bf16_f32 v3, v8, v9
	global_store_dwordx2 v[18:19], v[2:3], off offset:16
	v_cvt_pk_bf16_f32 v2, v10, v11
	v_cvt_pk_bf16_f32 v3, v12, v13
	global_store_dwordx2 v[18:19], v[2:3], off offset:32
	v_cvt_pk_bf16_f32 v2, v14, v15
	v_cvt_pk_bf16_f32 v3, v16, v17
	global_store_dwordx2 v[116:117], v[114:115], off
	global_store_dwordx2 v[18:19], v[2:3], off offset:48
	s_cbranch_scc0 .LBB0_53
